# L1 invalidate issued by wave 1 at grid-barrier entry, in parallel with thread 0's arrival/poll protocol; no post-release invalidate
# speedup vs baseline: 1.0535x; 1.0056x over previous
_Z11mega_kernel6Params:
	s_load_dwordx8 s[24:31], s[0:1], 0xe0
	s_load_dwordx8 s[4:11], s[0:1], 0xc0
	s_mov_b32 s16, s2
	s_add_u32 s2, s0, 0xf8
	s_addc_u32 s3, s1, 0
	v_and_b32_e32 v192, 0x3ff, v0
	v_readfirstlane_b32 s101, v192
	s_waitcnt lgkmcnt(0)
	v_writelane_b32 v252, s4, 0
	v_cmp_eq_u32_e64 s[66:67], 0, v192
	s_nop 0
	v_writelane_b32 v252, s5, 1
	v_writelane_b32 v252, s6, 2
	v_writelane_b32 v252, s7, 3
	v_writelane_b32 v252, s8, 4
	v_writelane_b32 v252, s9, 5
	v_writelane_b32 v252, s10, 6
	v_writelane_b32 v252, s11, 7
	v_writelane_b32 v252, s2, 8
	s_nop 1
	v_writelane_b32 v252, s3, 9
	s_and_saveexec_b64 s[2:3], s[66:67]
	s_cbranch_execz .LBB0_2
	s_add_i32 s4, 0, 0x24000
	v_mov_b32_e32 v2, 0
	v_mov_b32_e32 v3, v2
	v_mov_b32_e32 v4, v2
	v_mov_b32_e32 v5, v2
	v_mov_b32_e32 v1, s4
	ds_write_b128 v1, v[2:5]

.LBB0_150:
	s_getreg_b32 s2, hwreg(HW_REG_XCC_ID, 0, 4)
	s_waitcnt vmcnt(0)
	s_barrier
	s_cmp_lg_u32 s101, 64
	s_cbranch_scc1 .Lw1inv_skip_1
	buffer_inv sc1
	s_waitcnt vmcnt(0)
.Lw1inv_skip_1:
	s_and_saveexec_b64 s[0:1], s[66:67]
	s_cbranch_execz .LBB0_203
	s_add_i32 s3, 0, 0x24000
	v_mov_b32_e32 v0, s3
	s_waitcnt vmcnt(0) expcnt(0) lgkmcnt(0)
	ds_read_b32 v2, v0
	s_add_i32 s3, 0, 0x24004
	v_mov_b32_e32 v0, s3
	ds_read_b32 v0, v0
	s_and_b32 s17, s2, 15
	s_waitcnt lgkmcnt(1)
	v_cmp_ne_u32_e32 vcc, 0, v2
	s_cbranch_vccnz .LBB0_167
	s_add_u32 s2, s28, 0xee48200
	s_addc_u32 s3, s29, 0
	s_add_u32 s4, s28, 0xee48400
	s_addc_u32 s5, s29, 0
	s_add_u32 s6, s28, 0xee48500
	s_addc_u32 s7, s29, 0
	s_add_u32 s8, s28, 0xee48600
	s_addc_u32 s9, s29, 0
	s_add_u32 s10, s28, 0xee48700
	s_addc_u32 s11, s29, 0
	s_add_u32 s12, s28, 0xee48800
	s_addc_u32 s13, s29, 0
	s_add_u32 s14, s28, 0xee48900
	s_addc_u32 s15, s29, 0
	s_add_u32 s18, s28, 0xee48a00
	s_addc_u32 s19, s29, 0
	s_add_u32 s20, s28, 0xee48b00
	s_addc_u32 s21, s29, 0
	s_add_u32 s22, s28, 0xee48c00
	s_addc_u32 s23, s29, 0
	s_add_u32 s34, s28, 0xee48d00
	s_addc_u32 s35, s29, 0
	s_add_u32 s40, s28, 0xee48e00
	s_addc_u32 s41, s29, 0
	s_add_u32 s42, s28, 0xee48f00
	s_addc_u32 s43, s29, 0
	s_add_u32 s52, s28, 0xee49000
	s_addc_u32 s53, s29, 0
	s_add_u32 s54, s28, 0xee49100
	s_addc_u32 s55, s29, 0
	s_add_u32 s58, s28, 0xee49200
	s_addc_u32 s59, s29, 0
	s_mul_i32 s33, s31, s94
	s_add_u32 s60, s28, 0xee49300
	s_mul_i32 s33, s33, s30
	s_addc_u32 s61, s29, 0
	s_mov_b32 s68, 1
	v_mov_b32_e32 v16, 0
	s_branch .LBB0_155

.LBB0_200:
	s_or_b64 exec, exec, s[4:5]
	s_mov_b64 s[4:5], exec
	v_mbcnt_lo_u32_b32 v0, s4, 0
	v_mbcnt_hi_u32_b32 v0, s5, v0
	v_cmp_eq_u32_e32 vcc, 0, v0
	s_waitcnt vmcnt(0)

	s_and_saveexec_b64 s[6:7], vcc
	s_cbranch_execz .LBB0_202
	s_bcnt1_i32_b64 s4, s[4:5]
	v_mov_b32_e32 v0, 0x2000
	v_mov_b32_e32 v1, s4


.Lw1inv_skip_2:
	s_and_saveexec_b64 s[0:1], s[66:67]
	s_cbranch_execz .LBB0_288
	v_readlane_b32 s3, v254, 50
	s_waitcnt vmcnt(0) expcnt(0) lgkmcnt(0)
	s_and_b32 s14, s2, 15
	v_mov_b32_e32 v0, s3
	ds_read_b32 v3, v0
	v_readlane_b32 s3, v254, 51
	s_waitcnt lgkmcnt(0)
	v_cmp_ne_u32_e32 vcc, 0, v3
	v_mov_b32_e32 v0, s3
	ds_read_b32 v2, v0
	s_cbranch_vccnz .LBB0_252
	s_mov_b32 s18, 1
	s_branch .LBB0_240

.LBB0_285:
	s_or_b64 exec, exec, s[4:5]
	s_mov_b64 s[4:5], exec
	v_mbcnt_lo_u32_b32 v0, s4, 0
	v_mbcnt_hi_u32_b32 v0, s5, v0
	v_cmp_eq_u32_e32 vcc, 0, v0
	s_waitcnt vmcnt(0)

	s_and_saveexec_b64 s[6:7], vcc
	s_cbranch_execz .LBB0_287
	s_bcnt1_i32_b64 s4, s[4:5]
	v_mov_b32_e32 v0, s4


.LBB0_308:
	s_or_b64 exec, exec, s[18:19]
	s_getreg_b32 s2, hwreg(HW_REG_XCC_ID, 0, 4)
	s_waitcnt vmcnt(0)
	s_barrier
	s_cmp_lg_u32 s101, 64
	s_cbranch_scc1 .Lw1inv_skip_3
	buffer_inv sc1
	s_waitcnt vmcnt(0)

.LBB0_363:
	s_or_b64 exec, exec, s[0:1]
	s_getreg_b32 s2, hwreg(HW_REG_XCC_ID, 0, 4)
	s_waitcnt vmcnt(0)
	s_barrier
	s_cmp_lg_u32 s101, 64
	s_cbranch_scc1 .Lw1inv_skip_4
	buffer_inv sc1
	s_waitcnt vmcnt(0)

.LBB0_427:
	s_getreg_b32 s2, hwreg(HW_REG_XCC_ID, 0, 4)
	s_waitcnt vmcnt(0)
	s_waitcnt lgkmcnt(0)
	s_barrier
	s_cmp_lg_u32 s101, 64
	s_cbranch_scc1 .Lw1inv_skip_5
	buffer_inv sc1
	s_waitcnt vmcnt(0)

.LBB0_625:
	s_getreg_b32 s2, hwreg(HW_REG_XCC_ID, 0, 4)
	s_waitcnt vmcnt(0)
	s_waitcnt vmcnt(0) lgkmcnt(0)
	s_barrier
	s_cmp_lg_u32 s101, 64
	s_cbranch_scc1 .Lw1inv_skip_6
	buffer_inv sc1
	s_waitcnt vmcnt(0)

.LBB0_901:
	s_or_b64 exec, exec, s[2:3]
	s_getreg_b32 s2, hwreg(HW_REG_XCC_ID, 0, 4)
	s_waitcnt vmcnt(0)
	s_barrier
	s_cmp_lg_u32 s101, 64
	s_cbranch_scc1 .Lw1inv_skip_9
	buffer_inv sc1
	s_waitcnt vmcnt(0)

.Lw1inv_skip_10:
	s_and_saveexec_b64 s[0:1], s[66:67]
	s_cbranch_execz .LBB0_1038
	v_readlane_b32 s3, v254, 50
	s_waitcnt vmcnt(0) expcnt(0) lgkmcnt(0)
	s_and_b32 s14, s2, 15
	v_mov_b32_e32 v0, s3
	ds_read_b32 v3, v0
	v_readlane_b32 s3, v254, 51
	s_waitcnt lgkmcnt(0)
	v_cmp_ne_u32_e32 vcc, 0, v3
	v_mov_b32_e32 v0, s3
	ds_read_b32 v2, v0
	s_cbranch_vccnz .LBB0_1002
	s_mov_b32 s20, 1
	s_branch .LBB0_990

.LBB0_1035:
	s_or_b64 exec, exec, s[4:5]
	s_mov_b64 s[4:5], exec
	v_mbcnt_lo_u32_b32 v0, s4, 0
	v_mbcnt_hi_u32_b32 v0, s5, v0
	v_cmp_eq_u32_e32 vcc, 0, v0
	s_waitcnt vmcnt(0)

	s_and_saveexec_b64 s[18:19], vcc
	s_cbranch_execz .LBB0_1037
	s_bcnt1_i32_b64 s4, s[4:5]
	v_mov_b32_e32 v0, s4


.LBB0_1170:
	s_or_b64 exec, exec, s[4:5]
	s_mov_b64 s[4:5], exec
	v_mbcnt_lo_u32_b32 v0, s4, 0
	v_mbcnt_hi_u32_b32 v0, s5, v0
	v_cmp_eq_u32_e32 vcc, 0, v0
	s_waitcnt vmcnt(0)

	s_and_saveexec_b64 s[6:7], vcc
	s_cbranch_execz .LBB0_204
	s_bcnt1_i32_b64 s4, s[4:5]
	v_mov_b32_e32 v0, s4

	s_branch .LBB0_204

	.amdhsa_kernel _Z11mega_kernel6Params
		.amdhsa_group_segment_fixed_size 0
		.amdhsa_private_segment_fixed_size 0
		.amdhsa_kernarg_size 504
		.amdhsa_user_sgpr_count 2
		.amdhsa_user_sgpr_dispatch_ptr 0
		.amdhsa_user_sgpr_queue_ptr 0
		.amdhsa_user_sgpr_kernarg_segment_ptr 1
		.amdhsa_user_sgpr_dispatch_id 0
		.amdhsa_user_sgpr_kernarg_preload_length 0
		.amdhsa_user_sgpr_kernarg_preload_offset 0
		.amdhsa_user_sgpr_private_segment_size 0
		.amdhsa_uses_dynamic_stack 0
		.amdhsa_enable_private_segment 0
		.amdhsa_system_sgpr_workgroup_id_x 1
		.amdhsa_system_sgpr_workgroup_id_y 0
		.amdhsa_system_sgpr_workgroup_id_z 0
		.amdhsa_system_sgpr_workgroup_info 0
		.amdhsa_system_vgpr_workitem_id 2
		.amdhsa_next_free_vgpr 256
		.amdhsa_next_free_sgpr 102
		.amdhsa_accum_offset 256
		.amdhsa_reserve_vcc 1
		.amdhsa_float_round_mode_32 0
		.amdhsa_float_round_mode_16_64 0
		.amdhsa_float_denorm_mode_32 3
		.amdhsa_float_denorm_mode_16_64 3
		.amdhsa_dx10_clamp 1
		.amdhsa_ieee_mode 1
		.amdhsa_fp16_overflow 0
		.amdhsa_tg_split 0
		.amdhsa_exception_fp_ieee_invalid_op 0
		.amdhsa_exception_fp_denorm_src 0
		.amdhsa_exception_fp_ieee_div_zero 0
		.amdhsa_exception_fp_ieee_overflow 0
		.amdhsa_exception_fp_ieee_underflow 0
		.amdhsa_exception_fp_ieee_inexact 0
		.amdhsa_exception_int_div_zero 0
	.end_amdhsa_kernel

amdhsa.kernels:
  - .agpr_count:     0
    .args:
      - .offset:         0
        .size:           248
        .value_kind:     by_value
      - .offset:         248
        .size:           4
        .value_kind:     hidden_block_count_x
      - .offset:         252
        .size:           4
        .value_kind:     hidden_block_count_y
      - .offset:         256
        .size:           4
        .value_kind:     hidden_block_count_z
      - .offset:         260
        .size:           2
        .value_kind:     hidden_group_size_x
      - .offset:         262
        .size:           2
        .value_kind:     hidden_group_size_y
      - .offset:         264
        .size:           2
        .value_kind:     hidden_group_size_z
      - .offset:         266
        .size:           2
        .value_kind:     hidden_remainder_x
      - .offset:         268
        .size:           2
        .value_kind:     hidden_remainder_y
      - .offset:         270
        .size:           2
        .value_kind:     hidden_remainder_z
      - .offset:         288
        .size:           8
        .value_kind:     hidden_global_offset_x
      - .offset:         296
        .size:           8
        .value_kind:     hidden_global_offset_y
      - .offset:         304
        .size:           8
        .value_kind:     hidden_global_offset_z
      - .offset:         312
        .size:           2
        .value_kind:     hidden_grid_dims
      - .offset:         336
        .size:           8
        .value_kind:     hidden_multigrid_sync_arg
      - .offset:         368
        .size:           4
        .value_kind:     hidden_dynamic_lds_size
    .group_segment_fixed_size: 0
    .kernarg_segment_align: 8
    .kernarg_segment_size: 504
    .language:       OpenCL C
    .language_version:
      - 2
      - 0
    .max_flat_workgroup_size: 512
    .name:           _Z11mega_kernel6Params
    .private_segment_fixed_size: 0
    .sgpr_count:     108
    .sgpr_spill_count: 217
    .symbol:         _Z11mega_kernel6Params.kd
    .uniform_work_group_size: 1
    .uses_dynamic_stack: false
    .vgpr_count:     256
    .vgpr_spill_count: 0
    .wavefront_size: 64
